# v8 plus compute-dtype comment, and the serialized row-statistic loads (stage_dt epilogue, up_proj rstd) fetched as one batch
# speedup vs baseline: 1.0036x; 1.0036x over previous
.LBB0_266:
	s_ashr_i32 s9, s8, 31
	s_lshl_b64 s[4:5], s[8:9], 12
	v_lshl_add_u64 v[144:145], v[50:51], 0, s[4:5]
	v_add_co_u32_e32 v152, vcc, 0x8000, v144
	global_load_dwordx4 v[4:7], v[144:145], off
	global_load_dwordx4 v[8:11], v[24:25], off
	v_addc_co_u32_e32 v153, vcc, 0, v145, vcc
	v_add_co_u32_e32 v160, vcc, 0x10000, v144
	global_load_dwordx4 v[12:15], v[152:153], off
	s_nop 0
	v_addc_co_u32_e32 v161, vcc, 0, v145, vcc
	global_load_dwordx4 v[16:19], v[160:161], off
	global_load_dwordx4 v[56:59], v[26:27], off
	global_load_dwordx4 v[60:63], v[28:29], off
	global_load_dwordx4 v[64:67], v[30:31], off
	v_add_co_u32_e32 v164, vcc, 0x18000, v144
	v_add_u32_e32 v55, s20, v52
	s_nop 0
	v_addc_co_u32_e32 v165, vcc, 0, v145, vcc
	global_load_dwordx4 v[68:71], v[164:165], off
	global_load_dwordx4 v[72:75], v[144:145], off offset:128
	global_load_dwordx4 v[76:79], v[24:25], off offset:128
	global_load_dwordx4 v[80:83], v[152:153], off offset:128
	global_load_dwordx4 v[84:87], v[32:33], off
	global_load_dwordx4 v[88:91], v[160:161], off offset:128
	global_load_dwordx4 v[92:95], v[34:35], off
	global_load_dwordx4 v[96:99], v[164:165], off offset:128
	global_load_dwordx4 v[100:103], v[36:37], off
	global_load_dwordx4 v[104:107], v[38:39], off
	global_load_dwordx4 v[108:111], v[40:41], off
	global_load_dwordx4 v[112:115], v[24:25], off offset:256
	global_load_dwordx4 v[116:119], v[24:25], off offset:384
	global_load_dwordx4 v[120:123], v[42:43], off
	global_load_dwordx4 v[124:127], v[44:45], off
	global_load_dwordx4 v[128:131], v[144:145], off offset:256
	global_load_dwordx4 v[132:135], v[46:47], off
	global_load_dwordx4 v[136:139], v[48:49], off
	global_load_dwordx4 v[140:143], v[152:153], off offset:256
	s_nop 0
	global_load_dwordx4 v[144:147], v[144:145], off offset:384
	s_nop 0
	global_load_dwordx4 v[148:151], v[160:161], off offset:256
	s_nop 0
	global_load_dwordx4 v[152:155], v[152:153], off offset:384
	s_nop 0
	global_load_dwordx4 v[156:159], v[164:165], off offset:256
	s_nop 0
	global_load_dwordx4 v[160:163], v[160:161], off offset:384
	s_nop 0
	global_load_dwordx4 v[164:167], v[164:165], off offset:384
	s_waitcnt vmcnt(0)
	ds_write_b128 v53, v[8:11] offset:4608
	ds_write_b128 v53, v[56:59] offset:5760
	ds_write_b128 v53, v[60:63] offset:6912
	ds_write_b128 v53, v[64:67] offset:8064
	ds_write_b128 v53, v[4:7]
	ds_write_b128 v53, v[12:15] offset:1152
	ds_write_b128 v53, v[16:19] offset:2304
	ds_write_b128 v53, v[68:71] offset:3456
	s_waitcnt lgkmcnt(0)
	ds_read_b128 v[4:7], v54
	ds_read_b128 v[8:11], v54 offset:4608
	ds_read_b128 v[56:59], v54 offset:16
	ds_read_b128 v[60:63], v54 offset:4624
	s_waitcnt lgkmcnt(2)
	v_mfma_f32_32x32x16_bf16 v[4:19], v[4:7], v[8:11], 0
	s_waitcnt lgkmcnt(0)
	v_mfma_f32_32x32x16_bf16 v[4:19], v[56:59], v[60:63], v[4:19]
	ds_read_b128 v[56:59], v54 offset:32
	ds_read_b128 v[60:63], v54 offset:4640
	ds_read_b128 v[64:67], v54 offset:48
	ds_read_b128 v[68:71], v54 offset:4656
	ds_write_b128 v53, v[72:75]
	ds_write_b128 v53, v[76:79] offset:4608
	ds_write_b128 v53, v[80:83] offset:1152
	ds_write_b128 v53, v[84:87] offset:5760
	ds_write_b128 v53, v[88:91] offset:2304
	ds_write_b128 v53, v[92:95] offset:6912
	ds_write_b128 v53, v[96:99] offset:3456
	ds_write_b128 v53, v[100:103] offset:8064
	s_waitcnt lgkmcnt(0)
	s_waitcnt lgkmcnt(10)
	v_mfma_f32_32x32x16_bf16 v[4:19], v[56:59], v[60:63], v[4:19]
	s_waitcnt lgkmcnt(8)
	v_mfma_f32_32x32x16_bf16 v[4:19], v[64:67], v[68:71], v[4:19]
	ds_read_b128 v[56:59], v54
	ds_read_b128 v[60:63], v54 offset:4608
	ds_read_b128 v[64:67], v54 offset:16
	ds_read_b128 v[68:71], v54 offset:4624
	s_waitcnt lgkmcnt(2)
	v_mfma_f32_32x32x16_bf16 v[4:19], v[56:59], v[60:63], v[4:19]
	s_waitcnt lgkmcnt(0)
	v_mfma_f32_32x32x16_bf16 v[4:19], v[64:67], v[68:71], v[4:19]
	ds_read_b128 v[56:59], v54 offset:32
	ds_read_b128 v[60:63], v54 offset:4640
	ds_read_b128 v[64:67], v54 offset:48
	ds_read_b128 v[68:71], v54 offset:4656
	ds_write_b128 v53, v[128:131]
	ds_write_b128 v53, v[112:115] offset:4608
	ds_write_b128 v53, v[140:143] offset:1152
	ds_write_b128 v53, v[104:107] offset:5760
	ds_write_b128 v53, v[148:151] offset:2304
	ds_write_b128 v53, v[108:111] offset:6912
	ds_write_b128 v53, v[156:159] offset:3456
	ds_write_b128 v53, v[120:123] offset:8064
	s_waitcnt lgkmcnt(0)
	s_waitcnt lgkmcnt(10)
	v_mfma_f32_32x32x16_bf16 v[4:19], v[56:59], v[60:63], v[4:19]
	s_waitcnt lgkmcnt(8)
	v_mfma_f32_32x32x16_bf16 v[4:19], v[64:67], v[68:71], v[4:19]
	ds_read_b128 v[56:59], v54
	ds_read_b128 v[60:63], v54 offset:4608
	ds_read_b128 v[64:67], v54 offset:16
	ds_read_b128 v[68:71], v54 offset:4624
	s_waitcnt lgkmcnt(2)
	v_mfma_f32_32x32x16_bf16 v[4:19], v[56:59], v[60:63], v[4:19]
	s_waitcnt lgkmcnt(0)
	v_mfma_f32_32x32x16_bf16 v[4:19], v[64:67], v[68:71], v[4:19]
	ds_read_b128 v[56:59], v54 offset:32
	ds_read_b128 v[60:63], v54 offset:4640
	ds_read_b128 v[64:67], v54 offset:48
	ds_read_b128 v[68:71], v54 offset:4656
	ds_write_b128 v53, v[144:147]
	ds_write_b128 v53, v[116:119] offset:4608
	ds_write_b128 v53, v[152:155] offset:1152
	ds_write_b128 v53, v[124:127] offset:5760
	ds_write_b128 v53, v[160:163] offset:2304
	ds_write_b128 v53, v[132:135] offset:6912
	ds_write_b128 v53, v[164:167] offset:3456
	ds_write_b128 v53, v[136:139] offset:8064
	s_waitcnt lgkmcnt(0)
	s_waitcnt lgkmcnt(10)
	v_mfma_f32_32x32x16_bf16 v[4:19], v[56:59], v[60:63], v[4:19]
	s_waitcnt lgkmcnt(8)
	v_mfma_f32_32x32x16_bf16 v[4:19], v[64:67], v[68:71], v[4:19]
	ds_read_b128 v[56:59], v54
	ds_read_b128 v[60:63], v54 offset:4608
	ds_read_b128 v[64:67], v54 offset:16
	ds_read_b128 v[68:71], v54 offset:4624
	s_waitcnt lgkmcnt(2)
	v_mfma_f32_32x32x16_bf16 v[4:19], v[56:59], v[60:63], v[4:19]
	s_waitcnt lgkmcnt(0)
	v_mfma_f32_32x32x16_bf16 v[4:19], v[64:67], v[68:71], v[4:19]
	ds_read_b128 v[56:59], v54 offset:32
	ds_read_b128 v[60:63], v54 offset:4640
	ds_read_b128 v[64:67], v54 offset:48
	ds_read_b128 v[68:71], v54 offset:4656
	s_waitcnt lgkmcnt(2)
	v_mfma_f32_32x32x16_bf16 v[4:19], v[56:59], v[60:63], v[4:19]
	s_waitcnt lgkmcnt(0)
	v_mfma_f32_32x32x16_bf16 v[4:19], v[64:67], v[68:71], v[4:19]
	s_nop 11
	ds_write2st64_b32 v55, v4, v5 offset1:1
	ds_write2st64_b32 v55, v6, v7 offset0:2 offset1:3
	ds_write2st64_b32 v55, v8, v9 offset0:4 offset1:5
	ds_write2st64_b32 v55, v10, v11 offset0:6 offset1:7
	ds_write2st64_b32 v55, v12, v13 offset0:8 offset1:9
	ds_write2st64_b32 v55, v14, v15 offset0:10 offset1:11
	ds_write2st64_b32 v55, v16, v17 offset0:12 offset1:13
	ds_write2st64_b32 v55, v18, v19 offset0:14 offset1:15
	s_waitcnt lgkmcnt(0)
	s_waitcnt lgkmcnt(0)
	s_barrier
	s_and_saveexec_b64 s[18:19], s[6:7]
	s_cbranch_execz .LBB0_265
	v_add_u32_e32 v11, s21, v52
	ds_read2st64_b32 v[4:5], v11 offset0:2 offset1:3
	ds_read2st64_b32 v[6:7], v11 offset0:18 offset1:19
	ds_read2st64_b32 v[8:9], v11 offset0:34 offset1:35
	ds_read2st64_b32 v[12:13], v11 offset0:50 offset1:51
	ds_read2st64_b32 v[14:15], v11 offset0:66 offset1:67
	ds_read2st64_b32 v[16:17], v11 offset0:82 offset1:83
	ds_read2st64_b32 v[18:19], v11 offset0:98 offset1:99
	ds_read2st64_b32 v[56:57], v11 offset0:114 offset1:115
	s_waitcnt lgkmcnt(7)
	v_add_f32_e32 v5, 0, v5
	v_add_f32_e32 v4, 0, v4
	s_waitcnt lgkmcnt(6)
	v_add_f32_e32 v5, v5, v7
	v_add_f32_e32 v4, v4, v6
	s_waitcnt lgkmcnt(5)
	v_add_f32_e32 v5, v5, v9
	v_add_f32_e32 v4, v4, v8
	s_waitcnt lgkmcnt(4)
	v_add_f32_e32 v5, v5, v13
	v_add_f32_e32 v4, v4, v12
	s_waitcnt lgkmcnt(3)
	v_add_f32_e32 v5, v5, v15
	v_add_f32_e32 v4, v4, v14
	s_waitcnt lgkmcnt(2)
	v_add_f32_e32 v5, v5, v17
	v_add_f32_e32 v4, v4, v16
	s_waitcnt lgkmcnt(1)
	v_add_f32_e32 v5, v5, v19
	v_add_f32_e32 v4, v4, v18
	s_waitcnt lgkmcnt(0)
	v_add_f32_e32 v5, v5, v57
	v_add_f32_e32 v4, v4, v56
	v_add_f32_e32 v10, 0, v5
	v_add_f32_e32 v12, 0, v4
	ds_read2st64_b32 v[4:5], v11 offset1:1
	ds_read2st64_b32 v[6:7], v11 offset0:16 offset1:17
	ds_read2st64_b32 v[8:9], v11 offset0:32 offset1:33
	ds_read2st64_b32 v[14:15], v11 offset0:48 offset1:49
	ds_read2st64_b32 v[16:17], v11 offset0:64 offset1:65
	ds_read2st64_b32 v[18:19], v11 offset0:80 offset1:81
	ds_read2st64_b32 v[56:57], v11 offset0:96 offset1:97
	ds_read2st64_b32 v[58:59], v11 offset0:112 offset1:113
	s_waitcnt lgkmcnt(7)
	v_add_f32_e32 v4, 0, v4
	v_add_f32_e32 v5, 0, v5
	s_waitcnt lgkmcnt(6)
	v_add_f32_e32 v4, v4, v6
	v_add_f32_e32 v5, v5, v7
	s_waitcnt lgkmcnt(5)
	v_add_f32_e32 v4, v4, v8
	v_add_f32_e32 v5, v5, v9
	s_waitcnt lgkmcnt(4)
	v_add_f32_e32 v4, v4, v14
	v_add_f32_e32 v5, v5, v15
	s_waitcnt lgkmcnt(3)
	v_add_f32_e32 v4, v4, v16
	v_add_f32_e32 v5, v5, v17
	s_waitcnt lgkmcnt(2)
	v_add_f32_e32 v4, v4, v18
	v_add_f32_e32 v5, v5, v19
	s_waitcnt lgkmcnt(1)
	v_add_f32_e32 v4, v4, v56
	v_add_f32_e32 v5, v5, v57
	s_waitcnt lgkmcnt(0)
	v_add_f32_e32 v4, v4, v58
	v_add_f32_e32 v5, v5, v59
	v_add_f32_e32 v14, 0, v4
	v_add_u32_e32 v4, s8, v2
	v_add_f32_e32 v13, 0, v5
	v_ashrrev_i32_e32 v5, 31, v4
	v_lshl_add_u64 v[6:7], v[4:5], 2, s[16:17]
	v_mov_b32_e32 v220, v6
	v_mov_b32_e32 v221, v7
	v_add_co_u32_e32 v222, vcc, s23, v6
	s_nop 1
	v_addc_co_u32_e32 v223, vcc, 0, v7, vcc
	v_add_co_u32_e32 v224, vcc, s78, v6
	s_nop 1
	v_addc_co_u32_e32 v225, vcc, 0, v7, vcc
	v_add_co_u32_e32 v226, vcc, s24, v6
	s_nop 1
	v_addc_co_u32_e32 v227, vcc, 0, v7, vcc
	v_add_co_u32_e32 v228, vcc, s25, v6
	s_nop 1
	v_addc_co_u32_e32 v229, vcc, 0, v7, vcc
	v_add_co_u32_e32 v230, vcc, s26, v6
	s_nop 1
	v_addc_co_u32_e32 v231, vcc, 0, v7, vcc
	v_add_co_u32_e32 v232, vcc, s27, v6
	s_nop 1
	v_addc_co_u32_e32 v233, vcc, 0, v7, vcc
	v_add_co_u32_e32 v234, vcc, s28, v6
	s_nop 1
	v_addc_co_u32_e32 v235, vcc, 0, v7, vcc
	global_load_dword v176, v[220:221], off
	global_load_dword v177, v[222:223], off offset:128
	global_load_dword v178, v[224:225], off offset:256
	global_load_dword v179, v[226:227], off offset:384
	global_load_dword v180, v[228:229], off offset:512
	global_load_dword v181, v[230:231], off offset:640
	global_load_dword v182, v[232:233], off offset:768
	global_load_dword v183, v[234:235], off offset:896
	global_load_dword v184, v[220:221], off offset:4
	global_load_dword v185, v[222:223], off offset:132
	global_load_dword v186, v[224:225], off offset:260
	global_load_dword v187, v[226:227], off offset:388
	global_load_dword v188, v[228:229], off offset:516
	global_load_dword v189, v[230:231], off offset:644
	global_load_dword v190, v[232:233], off offset:772
	global_load_dword v191, v[234:235], off offset:900
	global_load_dword v192, v[220:221], off offset:8
	global_load_dword v193, v[222:223], off offset:136
	global_load_dword v194, v[224:225], off offset:264
	global_load_dword v195, v[226:227], off offset:392
	global_load_dword v196, v[228:229], off offset:520
	global_load_dword v197, v[230:231], off offset:648
	global_load_dword v198, v[232:233], off offset:776
	global_load_dword v199, v[234:235], off offset:904
	global_load_dword v200, v[220:221], off offset:12
	global_load_dword v201, v[222:223], off offset:140
	global_load_dword v202, v[224:225], off offset:268
	global_load_dword v203, v[226:227], off offset:396
	global_load_dword v204, v[228:229], off offset:524
	global_load_dword v205, v[230:231], off offset:652
	global_load_dword v206, v[232:233], off offset:780
	global_load_dword v207, v[234:235], off offset:908
	s_waitcnt vmcnt(0)
	v_mov_b32_e32 v8, v176
	global_load_dword v11, v[20:21], off
	s_mov_b32 s9, 0xbfb8aa3b
	s_waitcnt vmcnt(0) lgkmcnt(0)
	v_add_f32_e32 v15, 0, v8
	v_add_co_u32_e32 v8, vcc, s23, v6
	s_nop 1
	v_addc_co_u32_e32 v9, vcc, 0, v7, vcc
	v_mov_b32_e32 v8, v177
	s_waitcnt vmcnt(0) lgkmcnt(0)
	v_add_f32_e32 v15, v15, v8
	v_add_co_u32_e32 v8, vcc, s78, v6
	s_nop 1
	v_addc_co_u32_e32 v9, vcc, 0, v7, vcc
	v_mov_b32_e32 v8, v178
	s_waitcnt vmcnt(0) lgkmcnt(0)
	v_add_f32_e32 v15, v15, v8
	v_add_co_u32_e32 v8, vcc, s24, v6
	s_nop 1
	v_addc_co_u32_e32 v9, vcc, 0, v7, vcc
	v_mov_b32_e32 v8, v179
	s_waitcnt vmcnt(0) lgkmcnt(0)
	v_add_f32_e32 v15, v15, v8
	v_add_co_u32_e32 v8, vcc, s25, v6
	s_nop 1
	v_addc_co_u32_e32 v9, vcc, 0, v7, vcc
	v_mov_b32_e32 v8, v180
	s_waitcnt vmcnt(0) lgkmcnt(0)
	v_add_f32_e32 v15, v15, v8
	v_add_co_u32_e32 v8, vcc, s26, v6
	s_nop 1
	v_addc_co_u32_e32 v9, vcc, 0, v7, vcc
	v_mov_b32_e32 v8, v181
	s_waitcnt vmcnt(0) lgkmcnt(0)
	v_add_f32_e32 v15, v15, v8
	v_add_co_u32_e32 v8, vcc, s27, v6
	s_nop 1
	v_addc_co_u32_e32 v9, vcc, 0, v7, vcc
	v_add_co_u32_e32 v6, vcc, s28, v6
	v_mov_b32_e32 v8, v182
	s_nop 0
	v_addc_co_u32_e32 v7, vcc, 0, v7, vcc
	v_mov_b32_e32 v6, v183
	v_add_f32_e32 v8, v15, v8
	v_add_f32_e32 v6, v8, v6
	v_fmamk_f32 v6, v6, 0x3a000000, v214
	v_cmp_gt_f32_e32 vcc, s79, v6
	v_mul_f32_e32 v7, 0x4f800000, v6
	s_nop 0
	v_cndmask_b32_e32 v6, v6, v7, vcc
	v_sqrt_f32_e32 v7, v6
	s_nop 0
	v_add_u32_e32 v8, -1, v7
	v_fma_f32 v9, -v8, v7, v6
	v_cmp_ge_f32_e64 s[4:5], 0, v9
	v_add_u32_e32 v9, 1, v7
	s_nop 0
	v_cndmask_b32_e64 v8, v7, v8, s[4:5]
	v_fma_f32 v7, -v9, v7, v6
	v_cmp_lt_f32_e64 s[4:5], 0, v7
	s_nop 1
	v_cndmask_b32_e64 v7, v8, v9, s[4:5]
	v_mul_f32_e32 v8, 0x37800000, v7
	v_cndmask_b32_e32 v7, v7, v8, vcc
	v_cmp_class_f32_e32 vcc, v6, v1
	s_nop 1
	v_cndmask_b32_e32 v6, v7, v6, vcc
	v_div_scale_f32 v7, s[4:5], v6, v6, v14
	v_rcp_f32_e32 v8, v7
	s_nop 0
	v_fma_f32 v9, -v7, v8, 1.0
	v_fmac_f32_e32 v8, v9, v8
	v_div_scale_f32 v9, vcc, v14, v6, v14
	v_mul_f32_e32 v15, v9, v8
	v_fma_f32 v16, -v7, v15, v9
	v_fmac_f32_e32 v15, v16, v8
	v_fma_f32 v7, -v7, v15, v9
	v_div_fmas_f32 v7, v7, v8, v15
	v_div_fixup_f32 v6, v7, v6, v14
	v_add_f32_e32 v6, v11, v6
	v_max_f32_e32 v8, 0, v6
	v_mul_f32_e64 v6, |v6|, s9
	v_exp_f32_e32 v6, v6
	s_nop 0
	v_add_f32_e32 v6, 1.0, v6
	v_log_f32_e32 v6, v6
	s_nop 0
	v_fmac_f32_e32 v8, 0x3f317218, v6
	v_lshlrev_b64 v[6:7], 6, v[4:5]
	v_lshl_add_u64 v[6:7], v[22:23], 0, v[6:7]
	flat_store_dword v[6:7], v8
	v_add_u32_e32 v6, 1, v4
	v_ashrrev_i32_e32 v7, 31, v6
	v_lshl_add_u64 v[8:9], v[6:7], 2, s[16:17]
	v_add_co_u32_e32 v14, vcc, s23, v8
	v_mov_b32_e32 v5, v184
	s_nop 0
	v_addc_co_u32_e32 v15, vcc, 0, v9, vcc
	v_mov_b32_e32 v14, v185
	v_lshlrev_b64 v[6:7], 6, v[6:7]
	v_lshl_add_u64 v[6:7], v[22:23], 0, v[6:7]
	v_add_f32_e32 v5, 0, v5
	v_add_f32_e32 v5, v5, v14
	v_add_co_u32_e32 v14, vcc, s78, v8
	s_nop 1
	v_addc_co_u32_e32 v15, vcc, 0, v9, vcc
	v_mov_b32_e32 v14, v186
	v_add_f32_e32 v5, v5, v14
	v_add_co_u32_e32 v14, vcc, s24, v8
	s_nop 1
	v_addc_co_u32_e32 v15, vcc, 0, v9, vcc
	v_mov_b32_e32 v14, v187
	v_add_f32_e32 v5, v5, v14
	v_add_co_u32_e32 v14, vcc, s25, v8
	s_nop 1
	v_addc_co_u32_e32 v15, vcc, 0, v9, vcc
	v_mov_b32_e32 v14, v188
	v_add_f32_e32 v5, v5, v14
	v_add_co_u32_e32 v14, vcc, s26, v8
	s_nop 1
	v_addc_co_u32_e32 v15, vcc, 0, v9, vcc
	v_mov_b32_e32 v14, v189
	v_add_f32_e32 v5, v5, v14
	v_add_co_u32_e32 v14, vcc, s27, v8
	s_nop 1
	v_addc_co_u32_e32 v15, vcc, 0, v9, vcc
	v_add_co_u32_e32 v8, vcc, s28, v8
	v_mov_b32_e32 v14, v190
	s_nop 0
	v_addc_co_u32_e32 v9, vcc, 0, v9, vcc
	v_mov_b32_e32 v8, v191
	v_add_f32_e32 v5, v5, v14
	v_add_f32_e32 v5, v5, v8
	v_fmamk_f32 v5, v5, 0x3a000000, v214
	v_cmp_gt_f32_e32 vcc, s79, v5
	v_mul_f32_e32 v8, 0x4f800000, v5
	s_nop 0
	v_cndmask_b32_e32 v5, v5, v8, vcc
	v_sqrt_f32_e32 v8, v5
	s_nop 0
	v_add_u32_e32 v9, -1, v8
	v_fma_f32 v14, -v9, v8, v5
	v_cmp_ge_f32_e64 s[4:5], 0, v14
	v_add_u32_e32 v14, 1, v8
	s_nop 0
	v_cndmask_b32_e64 v9, v8, v9, s[4:5]
	v_fma_f32 v8, -v14, v8, v5
	v_cmp_lt_f32_e64 s[4:5], 0, v8
	s_nop 1
	v_cndmask_b32_e64 v8, v9, v14, s[4:5]
	v_mul_f32_e32 v9, 0x37800000, v8
	v_cndmask_b32_e32 v8, v8, v9, vcc
	v_cmp_class_f32_e32 vcc, v5, v1
	s_nop 1
	v_cndmask_b32_e32 v5, v8, v5, vcc
	v_div_scale_f32 v8, s[4:5], v5, v5, v13
	v_rcp_f32_e32 v9, v8
	s_nop 0
	v_fma_f32 v14, -v8, v9, 1.0
	v_fmac_f32_e32 v9, v14, v9
	v_div_scale_f32 v14, vcc, v13, v5, v13
	v_mul_f32_e32 v15, v14, v9
	v_fma_f32 v16, -v8, v15, v14
	v_fmac_f32_e32 v15, v16, v9
	v_fma_f32 v8, -v8, v15, v14
	v_div_fmas_f32 v8, v8, v9, v15
	v_div_fixup_f32 v5, v8, v5, v13
	v_add_f32_e32 v5, v11, v5
	v_max_f32_e32 v8, 0, v5
	v_mul_f32_e64 v5, |v5|, s9
	v_exp_f32_e32 v5, v5
	s_nop 0
	v_add_f32_e32 v5, 1.0, v5
	v_log_f32_e32 v5, v5
	s_nop 0
	v_fmac_f32_e32 v8, 0x3f317218, v5
	flat_store_dword v[6:7], v8
	v_add_u32_e32 v6, 2, v4
	v_ashrrev_i32_e32 v7, 31, v6
	v_lshl_add_u64 v[8:9], v[6:7], 2, s[16:17]
	v_add_co_u32_e32 v14, vcc, s23, v8
	v_mov_b32_e32 v5, v192
	s_nop 0
	v_addc_co_u32_e32 v15, vcc, 0, v9, vcc
	v_mov_b32_e32 v13, v193
	v_add_co_u32_e32 v14, vcc, s78, v8
	v_lshlrev_b64 v[6:7], 6, v[6:7]
	s_nop 0
	v_addc_co_u32_e32 v15, vcc, 0, v9, vcc
	v_add_u32_e32 v4, 3, v4
	v_lshl_add_u64 v[6:7], v[22:23], 0, v[6:7]
	v_add_f32_e32 v5, 0, v5
	v_add_f32_e32 v5, v5, v13
	v_mov_b32_e32 v13, v194
	v_add_co_u32_e32 v14, vcc, s24, v8
	v_add_f32_e32 v5, v5, v13
	v_addc_co_u32_e32 v15, vcc, 0, v9, vcc
	v_mov_b32_e32 v13, v195
	v_add_co_u32_e32 v14, vcc, s25, v8
	v_add_f32_e32 v5, v5, v13
	v_addc_co_u32_e32 v15, vcc, 0, v9, vcc
	v_mov_b32_e32 v13, v196
	v_add_co_u32_e32 v14, vcc, s26, v8
	v_add_f32_e32 v5, v5, v13
	v_addc_co_u32_e32 v15, vcc, 0, v9, vcc
	v_mov_b32_e32 v13, v197
	v_add_co_u32_e32 v14, vcc, s27, v8
	v_add_f32_e32 v5, v5, v13
	v_addc_co_u32_e32 v15, vcc, 0, v9, vcc
	v_add_co_u32_e32 v8, vcc, s28, v8
	v_mov_b32_e32 v13, v198
	s_nop 0
	v_addc_co_u32_e32 v9, vcc, 0, v9, vcc
	v_mov_b32_e32 v8, v199
	v_add_f32_e32 v5, v5, v13
	v_add_f32_e32 v5, v5, v8
	v_fmamk_f32 v5, v5, 0x3a000000, v214
	v_cmp_gt_f32_e32 vcc, s79, v5
	v_mul_f32_e32 v8, 0x4f800000, v5
	s_nop 0
	v_cndmask_b32_e32 v5, v5, v8, vcc
	v_sqrt_f32_e32 v8, v5
	s_nop 0
	v_add_u32_e32 v9, -1, v8
	v_fma_f32 v13, -v9, v8, v5
	v_cmp_ge_f32_e64 s[4:5], 0, v13
	v_add_u32_e32 v13, 1, v8
	s_nop 0
	v_cndmask_b32_e64 v9, v8, v9, s[4:5]
	v_fma_f32 v8, -v13, v8, v5
	v_cmp_lt_f32_e64 s[4:5], 0, v8
	s_nop 1
	v_cndmask_b32_e64 v8, v9, v13, s[4:5]
	v_mul_f32_e32 v9, 0x37800000, v8
	v_cndmask_b32_e32 v8, v8, v9, vcc
	v_cmp_class_f32_e32 vcc, v5, v1
	s_nop 1
	v_cndmask_b32_e32 v5, v8, v5, vcc
	v_div_scale_f32 v8, s[4:5], v5, v5, v12
	v_rcp_f32_e32 v9, v8
	s_nop 0
	v_fma_f32 v13, -v8, v9, 1.0
	v_fmac_f32_e32 v9, v13, v9
	v_div_scale_f32 v13, vcc, v12, v5, v12
	v_mul_f32_e32 v14, v13, v9
	v_fma_f32 v15, -v8, v14, v13
	v_fmac_f32_e32 v14, v15, v9
	v_fma_f32 v8, -v8, v14, v13
	v_div_fmas_f32 v8, v8, v9, v14
	v_div_fixup_f32 v5, v8, v5, v12
	v_add_f32_e32 v5, v11, v5
	v_max_f32_e32 v8, 0, v5
	v_mul_f32_e64 v5, |v5|, s9
	v_exp_f32_e32 v5, v5
	s_nop 0
	v_add_f32_e32 v5, 1.0, v5
	v_log_f32_e32 v5, v5
	s_nop 0
	v_fmac_f32_e32 v8, 0x3f317218, v5
	v_ashrrev_i32_e32 v5, 31, v4
	flat_store_dword v[6:7], v8
	v_lshl_add_u64 v[6:7], v[4:5], 2, s[16:17]
	v_mov_b32_e32 v8, v200
	v_lshlrev_b64 v[4:5], 6, v[4:5]
	v_lshl_add_u64 v[4:5], v[22:23], 0, v[4:5]
	v_add_f32_e32 v12, 0, v8
	v_add_co_u32_e32 v8, vcc, s23, v6
	s_nop 1
	v_addc_co_u32_e32 v9, vcc, 0, v7, vcc
	v_mov_b32_e32 v8, v201
	v_add_f32_e32 v12, v12, v8
	v_add_co_u32_e32 v8, vcc, s78, v6
	s_nop 1
	v_addc_co_u32_e32 v9, vcc, 0, v7, vcc
	v_mov_b32_e32 v8, v202
	v_add_f32_e32 v12, v12, v8
	v_add_co_u32_e32 v8, vcc, s24, v6
	s_nop 1
	v_addc_co_u32_e32 v9, vcc, 0, v7, vcc
	v_mov_b32_e32 v8, v203
	v_add_f32_e32 v12, v12, v8
	v_add_co_u32_e32 v8, vcc, s25, v6
	s_nop 1
	v_addc_co_u32_e32 v9, vcc, 0, v7, vcc
	v_mov_b32_e32 v8, v204
	v_add_f32_e32 v12, v12, v8
	v_add_co_u32_e32 v8, vcc, s26, v6
	s_nop 1
	v_addc_co_u32_e32 v9, vcc, 0, v7, vcc
	v_mov_b32_e32 v8, v205
	v_add_f32_e32 v12, v12, v8
	v_add_co_u32_e32 v8, vcc, s27, v6
	s_nop 1
	v_addc_co_u32_e32 v9, vcc, 0, v7, vcc
	v_add_co_u32_e32 v6, vcc, s28, v6
	v_mov_b32_e32 v8, v206
	s_nop 0
	v_addc_co_u32_e32 v7, vcc, 0, v7, vcc
	v_mov_b32_e32 v6, v207
	v_add_f32_e32 v8, v12, v8
	v_add_f32_e32 v6, v8, v6
	v_fmamk_f32 v6, v6, 0x3a000000, v214
	v_cmp_gt_f32_e32 vcc, s79, v6
	v_mul_f32_e32 v7, 0x4f800000, v6
	s_nop 0
	v_cndmask_b32_e32 v6, v6, v7, vcc
	v_sqrt_f32_e32 v7, v6
	s_nop 0
	v_add_u32_e32 v8, -1, v7
	v_fma_f32 v9, -v8, v7, v6
	v_cmp_ge_f32_e64 s[4:5], 0, v9
	v_add_u32_e32 v9, 1, v7
	s_nop 0
	v_cndmask_b32_e64 v8, v7, v8, s[4:5]
	v_fma_f32 v7, -v9, v7, v6
	v_cmp_lt_f32_e64 s[4:5], 0, v7
	s_nop 1
	v_cndmask_b32_e64 v7, v8, v9, s[4:5]
	v_mul_f32_e32 v8, 0x37800000, v7
	v_cndmask_b32_e32 v7, v7, v8, vcc
	v_cmp_class_f32_e32 vcc, v6, v1
	s_nop 1
	v_cndmask_b32_e32 v6, v7, v6, vcc
	v_div_scale_f32 v7, s[4:5], v6, v6, v10
	v_rcp_f32_e32 v8, v7
	s_nop 0
	v_fma_f32 v9, -v7, v8, 1.0
	v_fmac_f32_e32 v8, v9, v8
	v_div_scale_f32 v9, vcc, v10, v6, v10
	v_mul_f32_e32 v12, v9, v8
	v_fma_f32 v13, -v7, v12, v9
	v_fmac_f32_e32 v12, v13, v8
	v_fma_f32 v7, -v7, v12, v9
	v_div_fmas_f32 v7, v7, v8, v12
	v_div_fixup_f32 v6, v7, v6, v10
	v_add_f32_e32 v6, v11, v6
	v_max_f32_e32 v7, 0, v6
	v_mul_f32_e64 v6, |v6|, s9
	v_exp_f32_e32 v6, v6
	s_nop 0
	v_add_f32_e32 v6, 1.0, v6
	v_log_f32_e32 v6, v6
	s_nop 0
	v_fmac_f32_e32 v7, 0x3f317218, v6
	flat_store_dword v[4:5], v7
	s_branch .LBB0_265

.LBB0_1326:
	v_add_u32_e32 v6, 0x200, v6
	v_add_co_u32_e32 v220, vcc, 0xe8d5c680, v4
	s_nop 1
	v_addc_co_u32_e32 v221, vcc, -1, v5, vcc
	v_add_co_u32_e32 v222, vcc, 0xe8d64700, v4
	s_nop 1
	v_addc_co_u32_e32 v223, vcc, -1, v5, vcc
	v_add_co_u32_e32 v224, vcc, 0xe8d6c780, v4
	s_nop 1
	v_addc_co_u32_e32 v225, vcc, -1, v5, vcc
	v_add_co_u32_e32 v226, vcc, 0xe8d74800, v4
	s_nop 1
	v_addc_co_u32_e32 v227, vcc, -1, v5, vcc
	v_add_co_u32_e32 v228, vcc, 0xe8d7c880, v4
	s_nop 1
	v_addc_co_u32_e32 v229, vcc, -1, v5, vcc
	v_add_co_u32_e32 v230, vcc, 0xe8d84900, v4
	s_nop 1
	v_addc_co_u32_e32 v231, vcc, -1, v5, vcc
	v_add_co_u32_e32 v232, vcc, 0xe8d8c980, v4
	s_nop 1
	v_addc_co_u32_e32 v233, vcc, -1, v5, vcc
	v_add_co_u32_e32 v234, vcc, 0xe8d94a00, v4
	s_nop 1
	v_addc_co_u32_e32 v235, vcc, -1, v5, vcc
	global_load_dword v176, v[220:221], off
	global_load_dword v177, v[222:223], off
	global_load_dword v178, v[224:225], off
	global_load_dword v179, v[226:227], off
	global_load_dword v180, v[228:229], off
	global_load_dword v181, v[230:231], off
	global_load_dword v182, v[232:233], off
	global_load_dword v183, v[234:235], off
	s_waitcnt vmcnt(0)
	v_add_f32_e32 v7, 0, v176
	v_add_f32_e32 v7, v7, v177
	v_add_f32_e32 v7, v7, v178
	v_add_f32_e32 v7, v7, v179
	v_add_f32_e32 v7, v7, v180
	v_add_f32_e32 v7, v7, v181
	v_add_f32_e32 v7, v7, v182
	v_add_f32_e32 v7, v7, v183
	v_fmamk_f32 v7, v7, 0x3a000000, v214
	v_cmp_gt_f32_e32 vcc, s79, v7
	v_mul_f32_e32 v8, 0x4f800000, v7
	s_nop 0
	v_cndmask_b32_e32 v7, v7, v8, vcc
	v_sqrt_f32_e32 v8, v7
	s_nop 0
	v_add_u32_e32 v9, -1, v8
	v_fma_f32 v10, -v9, v8, v7
	v_cmp_ge_f32_e64 s[6:7], 0, v10
	v_add_u32_e32 v10, 1, v8
	s_nop 0
	v_cndmask_b32_e64 v9, v8, v9, s[6:7]
	v_fma_f32 v8, -v10, v8, v7
	v_cmp_lt_f32_e64 s[6:7], 0, v8
	s_nop 1
	v_cndmask_b32_e64 v8, v9, v10, s[6:7]
	v_mul_f32_e32 v9, 0x37800000, v8
	v_cndmask_b32_e32 v8, v8, v9, vcc
	v_cmp_class_f32_e32 vcc, v7, v1
	s_nop 1
	v_cndmask_b32_e32 v7, v8, v7, vcc
	v_div_scale_f32 v8, s[6:7], v7, v7, 1.0
	v_rcp_f32_e32 v9, v8
	s_nop 0
	v_fma_f32 v10, -v8, v9, 1.0
	v_fmac_f32_e32 v9, v10, v9
	v_div_scale_f32 v10, vcc, 1.0, v7, 1.0
	v_mul_f32_e32 v11, v10, v9
	v_fma_f32 v12, -v8, v11, v10
	v_fmac_f32_e32 v11, v12, v9
	v_fma_f32 v8, -v8, v11, v10
	v_div_fmas_f32 v8, v8, v9, v11
	v_div_fixup_f32 v7, v8, v7, 1.0
	v_cmp_le_i32_e32 vcc, s26, v6
	flat_store_dword v[4:5], v7
	v_lshl_add_u64 v[4:5], v[4:5], 0, s[44:45]
	s_or_b64 s[16:17], vcc, s[16:17]
	s_andn2_b64 exec, exec, s[16:17]
	s_cbranch_execnz .LBB0_1326
	s_branch .LBB0_1314
